# on top of v36: M4 items (1 SSD + 4 GLA per workgroup, uniform) assigned statically it = bid + k*gridDim instead of through the atomic queue
# baseline (speedup 1.0000x reference)
.LBB0_718:
	s_cmp_lt_i32 s94, 6
	s_cselect_b64 s[0:1], -1, 0
	s_cmp_gt_i32 s95, 5
	s_cselect_b64 s[2:3], -1, 0
	s_and_b64 s[0:1], s[0:1], s[2:3]
	s_andn2_b64 vcc, exec, s[0:1]
	s_cbranch_vccnz .LBB0_857
	s_mov_b64 s[0:1], s[76:77]
	s_load_dwordx2 s[92:93], s[0:1], 0xb0
	s_mov_b64 s[0:1], s[76:77]
	v_mov_b32_e32 v0, v216
	s_load_dword s2, s[76:77], 0xc0
	s_add_u32 s0, s76, 0xc0
	s_addc_u32 s1, s77, 0
	v_writelane_b32 v255, s0, 8
	s_waitcnt lgkmcnt(0)
	v_mbcnt_lo_u32_b32 v1, -1, 0
	s_mov_b32 s84, 0
	v_writelane_b32 v255, s1, 9
	s_mov_b32 s0, s2
	s_add_u32 s0, s92, 0x49300000
	v_writelane_b32 v255, s2, 10
	s_addc_u32 s1, s93, 0
	v_writelane_b32 v255, s0, 11
	v_mov_b32_e32 v0, 0
	s_movk_i32 s80, 0x5c00
	v_writelane_b32 v255, s1, 12
	s_add_u32 s0, s92, 0x33b00000
	v_writelane_b32 v255, s0, 13
	s_addc_u32 s0, s93, 0
	v_writelane_b32 v255, s0, 15
	s_add_u32 s0, s92, 0x2fb00000
	s_addc_u32 s1, s93, 0
	s_add_u32 s94, s92, 0x300000
	s_addc_u32 s95, s93, 0
	s_add_u32 s16, s92, 0x200000
	v_writelane_b32 v255, s0, 16
	s_addc_u32 s17, s93, 0
	s_mov_b64 s[18:19], 0x4b03800
	v_writelane_b32 v255, s1, 17
	s_add_u32 s0, s92, 0x2bb00060
	s_addc_u32 s1, s93, 0
	v_writelane_b32 v255, s0, 18
	s_add_i32 s81, 0, 0x20000
	v_mov_b32_e32 v87, s81
	v_writelane_b32 v255, s1, 19
	v_writelane_b32 v255, s16, 20
	v_mov_b32_e32 v120, 0x358637bd
	s_mov_b32 s20, 0x800000
	s_movk_i32 s21, 0x1ff
	s_movk_i32 s22, 0xc00
	s_mov_b64 s[24:25], 0x40b00800
	s_mov_b32 s33, 0x5040100
	s_mov_b32 s85, 0x43b00000
	s_mov_b32 s86, 0x43b01000
	s_mov_b64 s[2:3], 0x8000
	s_mov_b64 s[88:89], 0x100
	v_mbcnt_hi_u32_b32 v121, -1, v1
	v_writelane_b32 v255, s17, 21
	v_readlane_b32 s98, v255, 5
	v_readlane_b32 s99, v255, 6
	s_nop 4
	s_load_dword s99, s[98:99], 0xc0
	s_waitcnt lgkmcnt(0)
	v_readlane_b32 s98, v255, 7
	s_branch .LBB0_722

.LBB0_722:
	s_waitcnt vmcnt(0)
	s_barrier
	s_and_saveexec_b64 s[4:5], s[90:91]
	s_cbranch_execz .LBB0_726
	v_mov_b32_e32 v1, s98
	v_mov_b32_e32 v2, s81
	ds_write_b32 v2, v1
.LBB0_726:
	s_or_b64 exec, exec, s[4:5]
	s_add_u32 s98, s98, s99
	s_waitcnt lgkmcnt(0)
	s_barrier
	ds_read_b32 v1, v87
	s_movk_i32 s1, 0x4ff
	s_mov_b64 s[4:5], -1
	s_waitcnt lgkmcnt(0)
	v_cmp_lt_i32_e32 vcc, s1, v1
	v_readfirstlane_b32 s0, v1
	s_cbranch_vccnz .LBB0_721
	s_cmpk_gt_i32 s0, 0xff
	s_cbranch_scc0 .LBB0_754
	v_mov_b32_e32 v1, v216
	s_add_i32 s14, s0, 0xffffff00
	s_lshr_b32 s10, s14, 2
	v_readfirstlane_b32 s1, v1
	v_and_b32_e32 v24, 15, v1
	s_bfe_u32 s4, s1, 0x20006
	s_lshl_b32 s11, s4, 4
	v_lshl_or_b32 v25, s10, 6, v24
	v_or_b32_e32 v54, s11, v25
	v_mov_b64_e32 v[2:3], s[92:93]
	s_and_b32 s15, s0, 3
	v_mad_u64_u32 v[56:57], s[6:7], v54, s80, v[2:3]
	v_bfe_u32 v1, v1, 4, 2
	s_lshl_b32 s6, s15, 8
	s_mov_b32 s7, s84
	v_mad_u64_u32 v[2:3], s[8:9], v25, s80, v[2:3]
	v_lshlrev_b32_e32 v6, 4, v1
	v_mov_b32_e32 v7, v0
	v_lshl_add_u64 v[2:3], v[2:3], 0, s[6:7]
	v_lshl_add_u64 v[12:13], v[2:3], 0, v[6:7]
	s_mov_b32 s5, 0x4b03000
	v_add_co_u32_e32 v2, vcc, s5, v12
	v_lshl_add_u64 v[4:5], v[56:57], 0, s[6:7]
	s_nop 0
	v_addc_co_u32_e32 v3, vcc, 0, v13, vcc
	v_lshl_add_u64 v[10:11], v[4:5], 0, v[6:7]
	global_load_dwordx4 v[2:5], v[2:3], off offset:2048
	v_add_co_u32_e32 v6, vcc, s5, v10
	v_lshl_add_u64 v[12:13], v[12:13], 0, s[18:19]
	s_nop 0
	v_addc_co_u32_e32 v7, vcc, 0, v11, vcc
	global_load_dwordx4 v[6:9], v[6:7], off offset:1024
	s_mov_b64 s[8:9], 0x4b03400
	global_load_dwordx4 v[26:29], v[12:13], off offset:64
	global_load_dwordx4 v[30:33], v[12:13], off offset:128
	v_lshl_add_u64 v[18:19], v[10:11], 0, s[8:9]
	global_load_dwordx4 v[14:17], v[18:19], off offset:64
	global_load_dwordx4 v[34:37], v[12:13], off offset:192
	s_nop 0
	global_load_dwordx4 v[10:13], v[18:19], off offset:192
	s_lshl_b32 s5, s15, 7
	global_load_dwordx4 v[18:21], v[18:19], off offset:128
	v_lshlrev_b32_e32 v22, 3, v1
	v_or_b32_e32 v55, s11, v24
	v_lshlrev_b32_e32 v68, 2, v1
	s_cmp_eq_u32 s4, 0
	v_lshlrev_b32_e32 v22, 1, v22
	s_waitcnt vmcnt(6)
	v_mfma_f32_16x16x32_bf16 v[2:5], v[2:5], v[6:9], 0
	s_waitcnt vmcnt(3)
	v_mfma_f32_16x16x32_bf16 v[2:5], v[26:29], v[14:17], v[2:5]
	s_waitcnt vmcnt(0)
	v_mfma_f32_16x16x32_bf16 v[2:5], v[30:33], v[18:21], v[2:5]
	v_mfma_f32_16x16x32_bf16 v[2:5], v[34:37], v[10:13], v[2:5]
	s_cbranch_scc1 .LBB0_730
	v_or_b32_e32 v23, 16, v25
	v_mov_b64_e32 v[26:27], s[92:93]
	v_mad_u64_u32 v[26:27], s[8:9], v23, s80, v[26:27]
	s_lshl_b32 s8, s5, 1
	s_mov_b32 s9, s84
	v_lshl_add_u64 v[26:27], v[26:27], 0, s[8:9]
	v_mov_b32_e32 v23, v0
	v_lshl_add_u64 v[30:31], v[26:27], 0, v[22:23]
	v_add_co_u32_e32 v26, vcc, 0x4b03000, v30
	v_lshl_add_u64 v[38:39], v[30:31], 0, s[18:19]
	s_nop 0
	v_addc_co_u32_e32 v27, vcc, 0, v31, vcc
	global_load_dwordx4 v[26:29], v[26:27], off offset:2048
	s_nop 0
	global_load_dwordx4 v[30:33], v[38:39], off offset:64
	global_load_dwordx4 v[34:37], v[38:39], off offset:192
	v_or_b32_e32 v23, 16, v68
	global_load_dwordx4 v[38:41], v[38:39], off offset:128
	v_cmp_gt_u32_e32 vcc, v23, v55
	s_waitcnt vmcnt(3)
	v_mfma_f32_16x16x32_bf16 v[26:29], v[26:29], v[6:9], 0
	s_waitcnt vmcnt(2)
	v_mfma_f32_16x16x32_bf16 v[26:29], v[30:33], v[14:17], v[26:29]
	v_mov_b32_e32 v30, s84
	v_or_b32_e32 v31, 17, v68
	v_or_b32_e32 v32, 18, v68
	s_waitcnt vmcnt(0)
	v_mfma_f32_16x16x32_bf16 v[26:29], v[38:41], v[18:21], v[26:29]
	v_or_b32_e32 v33, 19, v68
	v_mfma_f32_16x16x32_bf16 v[26:29], v[34:37], v[10:13], v[26:29]
	s_nop 7
	v_cndmask_b32_e32 v26, v26, v30, vcc
	v_cmp_le_u32_e32 vcc, v31, v55
	s_nop 1
	v_cndmask_b32_e32 v27, 0, v27, vcc
	v_cmp_le_u32_e32 vcc, v32, v55
	s_nop 1
	v_cndmask_b32_e32 v28, 0, v28, vcc
	v_cmp_le_u32_e32 vcc, v33, v55
	s_nop 1
	v_cndmask_b32_e32 v29, 0, v29, vcc
	s_branch .LBB0_731

.LBB0_1773:
	s_cmp_lt_i32 s94, 14
	s_cselect_b64 s[0:1], -1, 0
	s_cmp_gt_i32 s95, 13
	s_cselect_b64 s[2:3], -1, 0
	s_and_b64 s[0:1], s[0:1], s[2:3]
	s_andn2_b64 vcc, exec, s[0:1]
	s_cbranch_vccnz .LBB0_1911
	s_mov_b64 s[0:1], s[76:77]
	s_load_dwordx2 s[92:93], s[0:1], 0xb0
	s_mov_b64 s[0:1], s[76:77]
	s_waitcnt vmcnt(0)
	v_mov_b32_e32 v0, v216
	s_load_dword s0, s[76:77], 0xc0
	s_add_u32 s2, s76, 0xc0
	s_addc_u32 s3, s77, 0
	v_writelane_b32 v255, s2, 22
	s_waitcnt lgkmcnt(0)
	v_mbcnt_lo_u32_b32 v1, -1, 0
	s_mov_b32 s84, 0
	v_writelane_b32 v255, s3, 23
	v_writelane_b32 v255, s0, 24
	s_add_u32 s0, s92, 0x49300000
	s_addc_u32 s1, s93, 0
	v_writelane_b32 v255, s0, 13
	v_mov_b32_e32 v0, 0
	s_movk_i32 s17, 0x5c00
	v_writelane_b32 v255, s1, 14
	s_add_u32 s0, s92, 0x33b00000
	v_writelane_b32 v255, s0, 15
	s_addc_u32 s0, s93, 0
	v_writelane_b32 v255, s0, 16
	s_add_u32 s0, s92, 0x2fb00000
	s_addc_u32 s1, s93, 0
	s_add_u32 s88, s92, 0x300000
	s_addc_u32 s89, s93, 0
	s_add_u32 s14, s92, 0x200000
	v_writelane_b32 v255, s0, 20
	s_addc_u32 s15, s93, 0
	s_mov_b64 s[18:19], 0x4b03800
	v_writelane_b32 v255, s1, 21
	s_add_u32 s0, s92, 0x2bb00060
	s_addc_u32 s1, s93, 0
	v_writelane_b32 v255, s0, 8
	s_add_i32 s16, 0, 0x20000
	v_mov_b32_e32 v87, s16
	v_writelane_b32 v255, s1, 9
	v_writelane_b32 v255, s14, 18
	v_mov_b32_e32 v120, 0x358637bd
	s_mov_b32 s20, 0x800000
	v_writelane_b32 v255, s15, 19
	s_movk_i32 s21, 0x1ff
	s_movk_i32 s22, 0xc00
	s_mov_b64 s[24:25], 0x40b00800
	s_mov_b32 s33, 0x5040100
	s_mov_b32 s85, 0x43b00000
	s_mov_b32 s86, 0x43b01000
	s_mov_b64 s[94:95], 0x8000
	s_mov_b64 s[96:97], 0x100
	v_mbcnt_hi_u32_b32 v121, -1, v1
	v_mov_b32_e32 v122, 0x1000
	v_writelane_b32 v255, s16, 10
	v_readlane_b32 s98, v255, 5
	v_readlane_b32 s99, v255, 6
	s_nop 4
	s_load_dword s99, s[98:99], 0xc0
	s_waitcnt lgkmcnt(0)
	v_readlane_b32 s98, v255, 7
	s_branch .LBB0_1777

.LBB0_1777:
	s_barrier
	s_and_saveexec_b64 s[2:3], s[90:91]
	s_cbranch_execz .LBB0_1781
	v_mov_b32_e32 v1, s98
	v_mov_b32_e32 v2, s16
	ds_write_b32 v2, v1
.LBB0_1781:
	s_or_b64 exec, exec, s[2:3]
	s_add_u32 s98, s98, s99
	s_waitcnt lgkmcnt(0)
	s_barrier
	ds_read_b32 v1, v87
	s_movk_i32 s1, 0x4ff
	s_mov_b64 s[2:3], -1
	s_waitcnt lgkmcnt(0)
	v_cmp_lt_i32_e32 vcc, s1, v1
	v_readfirstlane_b32 s0, v1
	s_cbranch_vccnz .LBB0_1776
	s_cmpk_gt_i32 s0, 0xff
	s_cbranch_scc0 .LBB0_1809
	v_mov_b32_e32 v1, v216
	s_add_i32 s12, s0, 0xffffff00
	s_lshr_b32 s8, s12, 2
	v_readfirstlane_b32 s1, v1
	v_and_b32_e32 v24, 15, v1
	s_bfe_u32 s4, s1, 0x20006
	s_lshl_b32 s5, s4, 4
	v_lshl_or_b32 v25, s8, 6, v24
	v_or_b32_e32 v54, s5, v25
	v_mov_b64_e32 v[2:3], s[92:93]
	s_and_b32 s13, s0, 3
	v_mad_u64_u32 v[56:57], s[2:3], v54, s17, v[2:3]
	v_bfe_u32 v1, v1, 4, 2
	s_lshl_b32 s2, s13, 8
	s_mov_b32 s3, s84
	v_mad_u64_u32 v[2:3], s[6:7], v25, s17, v[2:3]
	v_lshlrev_b32_e32 v6, 4, v1
	v_mov_b32_e32 v7, v0
	v_lshl_add_u64 v[2:3], v[2:3], 0, s[2:3]
	v_lshl_add_u64 v[4:5], v[56:57], 0, s[2:3]
	v_lshl_add_u64 v[12:13], v[2:3], 0, v[6:7]
	s_mov_b32 s3, 0x4b03000
	v_add_co_u32_e32 v2, vcc, s3, v12
	v_lshl_add_u64 v[10:11], v[4:5], 0, v[6:7]
	s_nop 0
	v_addc_co_u32_e32 v3, vcc, 0, v13, vcc
	global_load_dwordx4 v[2:5], v[2:3], off offset:2048
	v_add_co_u32_e32 v6, vcc, s3, v10
	v_lshl_add_u64 v[12:13], v[12:13], 0, s[18:19]
	s_nop 0
	v_addc_co_u32_e32 v7, vcc, 0, v11, vcc
	global_load_dwordx4 v[6:9], v[6:7], off offset:1024
	s_mov_b64 s[6:7], 0x4b03400
	global_load_dwordx4 v[26:29], v[12:13], off offset:64
	global_load_dwordx4 v[30:33], v[12:13], off offset:128
	v_lshl_add_u64 v[18:19], v[10:11], 0, s[6:7]
	global_load_dwordx4 v[14:17], v[18:19], off offset:64
	global_load_dwordx4 v[34:37], v[12:13], off offset:192
	s_nop 0
	global_load_dwordx4 v[10:13], v[18:19], off offset:192
	s_lshl_b32 s3, s13, 7
	global_load_dwordx4 v[18:21], v[18:19], off offset:128
	v_lshlrev_b32_e32 v22, 3, v1
	v_or_b32_e32 v55, s5, v24
	v_lshlrev_b32_e32 v68, 2, v1
	s_cmp_eq_u32 s4, 0
	v_lshlrev_b32_e32 v22, 1, v22
	s_waitcnt vmcnt(6)
	v_mfma_f32_16x16x32_bf16 v[2:5], v[2:5], v[6:9], 0
	s_waitcnt vmcnt(3)
	v_mfma_f32_16x16x32_bf16 v[2:5], v[26:29], v[14:17], v[2:5]
	s_waitcnt vmcnt(0)
	v_mfma_f32_16x16x32_bf16 v[2:5], v[30:33], v[18:21], v[2:5]
	v_mfma_f32_16x16x32_bf16 v[2:5], v[34:37], v[10:13], v[2:5]
	s_cbranch_scc1 .LBB0_1785
	v_or_b32_e32 v23, 16, v25
	v_mov_b64_e32 v[26:27], s[92:93]
	v_mad_u64_u32 v[26:27], s[6:7], v23, s17, v[26:27]
	s_lshl_b32 s6, s3, 1
	s_mov_b32 s7, s84
	v_lshl_add_u64 v[26:27], v[26:27], 0, s[6:7]
	v_mov_b32_e32 v23, v0
	v_lshl_add_u64 v[30:31], v[26:27], 0, v[22:23]
	v_add_co_u32_e32 v26, vcc, 0x4b03000, v30
	v_lshl_add_u64 v[38:39], v[30:31], 0, s[18:19]
	s_nop 0
	v_addc_co_u32_e32 v27, vcc, 0, v31, vcc
	global_load_dwordx4 v[26:29], v[26:27], off offset:2048
	s_nop 0
	global_load_dwordx4 v[30:33], v[38:39], off offset:64
	global_load_dwordx4 v[34:37], v[38:39], off offset:192
	v_or_b32_e32 v23, 16, v68
	global_load_dwordx4 v[38:41], v[38:39], off offset:128
	v_cmp_gt_u32_e32 vcc, v23, v55
	s_waitcnt vmcnt(3)
	v_mfma_f32_16x16x32_bf16 v[26:29], v[26:29], v[6:9], 0
	s_waitcnt vmcnt(2)
	v_mfma_f32_16x16x32_bf16 v[26:29], v[30:33], v[14:17], v[26:29]
	v_mov_b32_e32 v30, s84
	v_or_b32_e32 v31, 17, v68
	v_or_b32_e32 v32, 18, v68
	s_waitcnt vmcnt(0)
	v_mfma_f32_16x16x32_bf16 v[26:29], v[38:41], v[18:21], v[26:29]
	v_or_b32_e32 v33, 19, v68
	v_mfma_f32_16x16x32_bf16 v[26:29], v[34:37], v[10:13], v[26:29]
	s_nop 7
	v_cndmask_b32_e32 v26, v26, v30, vcc
	v_cmp_le_u32_e32 vcc, v31, v55
	s_nop 1
	v_cndmask_b32_e32 v27, 0, v27, vcc
	v_cmp_le_u32_e32 vcc, v32, v55
	s_nop 1
	v_cndmask_b32_e32 v28, 0, v28, vcc
	v_cmp_le_u32_e32 vcc, v33, v55
	s_nop 1
	v_cndmask_b32_e32 v29, 0, v29, vcc
	s_branch .LBB0_1786
